# NSA unit: rope-table batch 2 and first selected tile loads issued together with batch 1 (one round trip instead of three)
# baseline (speedup 1.0000x reference)
; DI float bf2f(bf16 b) { return __uint_as_float(((unsigned)b) << 16); }
; DI void nsa_unit(const Ctx& c0, int b, int g, int i, LAS unsigned char* lds) {
;     ...
;     { const float* ct = (const float*)(c.ws + O_TAB) + (size_t)t * 32; const float* stb = ct + 4096 * 32;
; #pragma unroll
;       for (int s = 0; s < 2; ++s) {
;           const f32x4 c0 = *(const f32x4*)(ct + 16 * s + 8 * hi), c1 = *(const f32x4*)(ct + 16 * s + 8 * hi + 4);
;           const f32x4 s0 = *(const f32x4*)(stb + 16 * s + 8 * hi), s1 = *(const f32x4*)(stb + 16 * s + 8 * hi + 4);
;           float lo_[8], hi_[8], ol[8], oh[8];
; #pragma unroll
;           for (int j = 0; j < 8; ++j) { lo_[j] = bf2f((bf16)qn[s][j]); hi_[j] = bf2f((bf16)qn[s + 2][j]); }
; #pragma unroll
;           for (int j = 0; j < 8; ++j) { const float cc = j < 4 ? c0[j & 3] : c1[j & 3], ss = j < 4 ? s0[j & 3] : s1[j & 3];
;               ol[j] = lo_[j] * cc - hi_[j] * ss; oh[j] = hi_[j] * cc + lo_[j] * ss; }
;           qr[s] = pack8(ol[0], ol[1], ol[2], ol[3], ol[4], ol[5], ol[6], ol[7]); qr[s + 2] = pack8(oh[0], oh[1], oh[2], oh[3], oh[4], oh[5], oh[6], oh[7]); } }
;     ...
;     {
;         const bf16* Kg = (const bf16*)(c.ws + O_KS) + ((size_t)g * T + (size_t)b * SEQ) * 64;
;         const bf16* Vg = (const bf16*)(c.ws + O_VS) + ((size_t)g * T + (size_t)b * SEQ) * 64;
;         ASt st; st.m = NEGB; st.l = 0.f; st.o0 = f32x16{}; st.o1 = f32x16{};
;         unsigned long long rem = um;
;         int n = __builtin_ctzll(rem); rem &= rem - 1ull;
;         TileRegs tr = tile_fetch(Kg, Vg, 64 * n, tid);
.LBB0_565:
	v_lshlrev_b64 v[4:5], 7, v[2:3]
	v_lshl_add_u64 v[4:5], s[0:1], 0, v[4:5]
	v_lshlrev_b32_e32 v2, 2, v124
	v_lshl_add_u64 v[16:17], v[4:5], 0, v[2:3]
	s_mov_b64 s[12:13], 0x2200000
	v_add_co_u32_e32 v4, vcc, 0x2200000, v16
	v_lshl_add_u64 v[24:25], v[16:17], 0, s[12:13]
	s_mov_b64 s[12:13], 0x2280000
	v_addc_co_u32_e32 v5, vcc, 0, v17, vcc
	v_lshl_add_u64 v[14:15], v[16:17], 0, s[12:13]
	v_add_co_u32_e32 v16, vcc, 0x2280000, v16
	global_load_dwordx4 v[4:7], v[4:5], off
	s_nop 0
	global_load_dwordx4 v[8:11], v[24:25], off offset:16
	v_addc_co_u32_e32 v17, vcc, 0, v17, vcc
	global_load_dwordx4 v[16:19], v[16:17], off
	s_nop 0
	global_load_dwordx4 v[20:23], v[14:15], off offset:16
	global_load_dwordx4 v[230:233], v[24:25], off offset:64
	global_load_dwordx4 v[234:237], v[24:25], off offset:80
	global_load_dwordx4 v[238:241], v[14:15], off offset:64
	global_load_dwordx4 v[242:245], v[14:15], off offset:80
	v_and_b32_e32 v29, 0xffff0000, v108
	v_lshlrev_b32_e32 v28, 16, v108
	v_and_b32_e32 v27, 0xffff0000, v112
	v_lshlrev_b32_e32 v26, 16, v112
	v_ffbl_b32_e32 v2, v13
	s_add_u32 s12, s0, s94
	v_add_u32_e32 v2, 32, v2
	s_addc_u32 s13, s1, s95
	s_add_u32 s88, s12, 0x8400000
	s_addc_u32 s89, s13, 0
	s_add_u32 s90, s12, 0x9400000
	s_addc_u32 s91, s13, 0
	s_mov_b32 s3, 0
	s_mov_b64 s[12:13], 0
	v_ffbl_b32_e32 v246, v12
	v_min_u32_e32 v52, v246, v2
	v_lshl_add_u32 v246, v52, 6, v140
	v_ashrrev_i32_e32 v247, 31, v246
	v_lshlrev_b64 v[246:247], 7, v[246:247]
	v_lshl_or_b32 v246, v138, 1, v246
	v_lshl_add_u64 v[248:249], s[88:89], 0, v[246:247]
	v_lshl_add_u64 v[246:247], s[90:91], 0, v[246:247]
	global_load_dwordx4 v[54:57], v[248:249], off
	global_load_dwordx4 v[58:61], v[246:247], off
	s_waitcnt vmcnt(6) lgkmcnt(0)
	v_pk_mul_f32 v[30:31], v[16:17], v[28:29]
	s_nop 0
	v_pk_fma_f32 v[30:31], v[4:5], v[26:27], v[30:31] neg_lo:[0,0,1] neg_hi:[0,0,1]
	v_pk_mul_f32 v[16:17], v[16:17], v[26:27]
	v_and_b32_e32 v27, 0xffff0000, v109
	v_lshlrev_b32_e32 v26, 16, v109
	v_pk_fma_f32 v[4:5], v[4:5], v[28:29], v[16:17]
	v_and_b32_e32 v17, 0xffff0000, v113
	v_lshlrev_b32_e32 v16, 16, v113
	v_pk_mul_f32 v[28:29], v[18:19], v[26:27]
	v_cvt_pk_bf16_f32 v86, v4, v5
	v_pk_fma_f32 v[28:29], v[6:7], v[16:17], v[28:29] neg_lo:[0,0,1] neg_hi:[0,0,1]
	v_pk_mul_f32 v[16:17], v[18:19], v[16:17]
	v_and_b32_e32 v19, 0xffff0000, v110
	v_lshlrev_b32_e32 v18, 16, v110
	v_pk_fma_f32 v[6:7], v[6:7], v[26:27], v[16:17]
	v_and_b32_e32 v17, 0xffff0000, v114
	v_lshlrev_b32_e32 v16, 16, v114
	v_pk_mul_f32 v[26:27], v[20:21], v[18:19]
	v_cvt_pk_bf16_f32 v87, v6, v7
	v_pk_fma_f32 v[26:27], v[8:9], v[16:17], v[26:27] neg_lo:[0,0,1] neg_hi:[0,0,1]
	v_pk_mul_f32 v[16:17], v[20:21], v[16:17]
	v_cvt_pk_bf16_f32 v84, v26, v27
	v_pk_fma_f32 v[8:9], v[8:9], v[18:19], v[16:17]
	v_and_b32_e32 v19, 0xffff0000, v111
	v_lshlrev_b32_e32 v18, 16, v111
	v_and_b32_e32 v17, 0xffff0000, v115
	v_lshlrev_b32_e32 v16, 16, v115
	v_pk_mul_f32 v[20:21], v[22:23], v[18:19]
	v_cvt_pk_bf16_f32 v88, v8, v9
	v_pk_fma_f32 v[20:21], v[10:11], v[16:17], v[20:21] neg_lo:[0,0,1] neg_hi:[0,0,1]
	v_pk_mul_f32 v[16:17], v[22:23], v[16:17]
	v_cvt_pk_bf16_f32 v85, v20, v21
	v_pk_fma_f32 v[10:11], v[10:11], v[18:19], v[16:17]
	v_cvt_pk_bf16_f32 v82, v30, v31
	v_cvt_pk_bf16_f32 v89, v10, v11
	v_and_b32_e32 v25, 0xffff0000, v104
	v_lshlrev_b32_e32 v24, 16, v104
	v_and_b32_e32 v15, 0xffff0000, v100
	v_lshlrev_b32_e32 v14, 16, v100
	v_cvt_pk_bf16_f32 v83, v28, v29
	s_waitcnt vmcnt(2) lgkmcnt(0)
	v_pk_mul_f32 v[26:27], v[238:239], v[24:25]
	s_nop 0
	v_pk_fma_f32 v[26:27], v[230:231], v[14:15], v[26:27] neg_lo:[0, 0, 1] neg_hi:[0, 0, 1]
	v_pk_mul_f32 v[14:15], v[238:239], v[14:15]
	v_and_b32_e32 v17, 0xffff0000, v105
	v_lshlrev_b32_e32 v16, 16, v105
	v_pk_fma_f32 v[8:9], v[230:231], v[24:25], v[14:15]
	v_and_b32_e32 v15, 0xffff0000, v101
	v_lshlrev_b32_e32 v14, 16, v101
	v_pk_mul_f32 v[24:25], v[240:241], v[16:17]
	v_cvt_pk_bf16_f32 v90, v26, v27
	v_pk_fma_f32 v[24:25], v[232:233], v[14:15], v[24:25] neg_lo:[0, 0, 1] neg_hi:[0, 0, 1]
	v_pk_mul_f32 v[14:15], v[240:241], v[14:15]
	v_cvt_pk_bf16_f32 v91, v24, v25
	v_pk_fma_f32 v[10:11], v[232:233], v[16:17], v[14:15]
	v_and_b32_e32 v17, 0xffff0000, v106
	v_lshlrev_b32_e32 v16, 16, v106
	v_and_b32_e32 v15, 0xffff0000, v102
	v_lshlrev_b32_e32 v14, 16, v102
	v_pk_mul_f32 v[18:19], v[242:243], v[16:17]
	v_cvt_pk_bf16_f32 v94, v8, v9
	v_pk_fma_f32 v[18:19], v[234:235], v[14:15], v[18:19] neg_lo:[0, 0, 1] neg_hi:[0, 0, 1]
	v_pk_mul_f32 v[14:15], v[242:243], v[14:15]
	v_cvt_pk_bf16_f32 v92, v18, v19
	v_pk_fma_f32 v[4:5], v[234:235], v[16:17], v[14:15]
	v_and_b32_e32 v17, 0xffff0000, v107
	v_cvt_pk_bf16_f32 v96, v4, v5
	v_lshl_add_u64 v[4:5], v[12:13], 0, -1
	v_lshlrev_b32_e32 v16, 16, v107
	v_and_b32_e32 v50, v4, v12
	v_and_b32_e32 v15, 0xffff0000, v103
	v_lshlrev_b32_e32 v14, 16, v103
	v_pk_mul_f32 v[20:21], v[244:245], v[16:17]
	v_and_b32_e32 v51, v5, v13
	v_pk_fma_f32 v[20:21], v[236:237], v[14:15], v[20:21] neg_lo:[0, 0, 1] neg_hi:[0, 0, 1]
	v_pk_mul_f32 v[14:15], v[244:245], v[14:15]
	v_pk_fma_f32 v[6:7], v[236:237], v[16:17], v[14:15]
	v_cvt_pk_bf16_f32 v97, v6, v7
	v_mov_b32_e32 v16, v3
	v_mov_b32_e32 v17, v3
	v_cvt_pk_bf16_f32 v93, v20, v21
	v_cvt_pk_bf16_f32 v95, v10, v11
	v_mov_b32_e32 v2, v3
	v_mov_b32_e32 v4, v3
	v_mov_b32_e32 v5, v3
	v_mov_b32_e32 v6, v3
	v_mov_b32_e32 v7, v3
	v_mov_b32_e32 v8, v3
	v_mov_b32_e32 v9, v3
	v_mov_b32_e32 v10, v3
	v_mov_b32_e32 v11, v3
	v_mov_b32_e32 v12, v3
	v_mov_b32_e32 v13, v3
	v_mov_b32_e32 v14, v3
	v_mov_b32_e32 v15, v3
	v_mov_b64_e32 v[32:33], v[16:17]
	v_mov_b64_e32 v[48:49], v[16:17]
	v_mov_b32_e32 v107, 0xf149f2ca
	v_mov_b32_e32 v106, 0
	v_mov_b64_e32 v[30:31], v[14:15]
	v_mov_b64_e32 v[28:29], v[12:13]
	v_mov_b64_e32 v[26:27], v[10:11]
	v_mov_b64_e32 v[24:25], v[8:9]
	v_mov_b64_e32 v[22:23], v[6:7]
	v_mov_b64_e32 v[20:21], v[4:5]
	v_mov_b64_e32 v[18:19], v[2:3]
	v_mov_b64_e32 v[46:47], v[14:15]
	v_mov_b64_e32 v[44:45], v[12:13]
	v_mov_b64_e32 v[42:43], v[10:11]
	v_mov_b64_e32 v[40:41], v[8:9]
	v_mov_b64_e32 v[38:39], v[6:7]
	v_mov_b64_e32 v[36:37], v[4:5]
	v_mov_b64_e32 v[34:35], v[2:3]
	s_waitcnt vmcnt(0)
	v_mov_b64_e32 v[98:99], v[54:55]
	v_mov_b64_e32 v[100:101], v[56:57]
	v_mov_b64_e32 v[102:103], v[58:59]
	v_mov_b64_e32 v[104:105], v[60:61]
	v_readfirstlane_b32 s98, v50
	v_readfirstlane_b32 s99, v51
	v_readfirstlane_b32 s100, v52
	s_branch .LBB0_568

; DI float bf2f(bf16 b) { return __uint_as_float(((unsigned)b) << 16); }
; DI void nsa_unit(const Ctx& c0, int b, int g, int i, LAS unsigned char* lds) {
;     ...
;     { const float* ct = (const float*)(c.ws + O_TAB) + (size_t)t * 32; const float* stb = ct + 4096 * 32;
; #pragma unroll
;       for (int s = 0; s < 2; ++s) {
;           const f32x4 c0 = *(const f32x4*)(ct + 16 * s + 8 * hi), c1 = *(const f32x4*)(ct + 16 * s + 8 * hi + 4);
;           const f32x4 s0 = *(const f32x4*)(stb + 16 * s + 8 * hi), s1 = *(const f32x4*)(stb + 16 * s + 8 * hi + 4);
;           float lo_[8], hi_[8], ol[8], oh[8];
; #pragma unroll
;           for (int j = 0; j < 8; ++j) { lo_[j] = bf2f((bf16)qn[s][j]); hi_[j] = bf2f((bf16)qn[s + 2][j]); }
; #pragma unroll
;           for (int j = 0; j < 8; ++j) { const float cc = j < 4 ? c0[j & 3] : c1[j & 3], ss = j < 4 ? s0[j & 3] : s1[j & 3];
;               ol[j] = lo_[j] * cc - hi_[j] * ss; oh[j] = hi_[j] * cc + lo_[j] * ss; }
;           qr[s] = pack8(ol[0], ol[1], ol[2], ol[3], ol[4], ol[5], ol[6], ol[7]); qr[s + 2] = pack8(oh[0], oh[1], oh[2], oh[3], oh[4], oh[5], oh[6], oh[7]); } }
;     ...
;     {
;         const bf16* Kg = (const bf16*)(c.ws + O_KS) + ((size_t)g * T + (size_t)b * SEQ) * 64;
;         const bf16* Vg = (const bf16*)(c.ws + O_VS) + ((size_t)g * T + (size_t)b * SEQ) * 64;
;         ASt st; st.m = NEGB; st.l = 0.f; st.o0 = f32x16{}; st.o1 = f32x16{};
;         unsigned long long rem = um;
;         int n = __builtin_ctzll(rem); rem &= rem - 1ull;
;         TileRegs tr = tile_fetch(Kg, Vg, 64 * n, tid);
.LBB0_1178:
	v_lshlrev_b64 v[4:5], 7, v[2:3]
	v_lshl_add_u64 v[4:5], s[0:1], 0, v[4:5]
	v_lshlrev_b32_e32 v2, 2, v124
	v_lshl_add_u64 v[16:17], v[4:5], 0, v[2:3]
	s_mov_b64 s[14:15], 0x2200000
	v_add_co_u32_e32 v4, vcc, 0x2200000, v16
	v_lshl_add_u64 v[24:25], v[16:17], 0, s[14:15]
	s_mov_b64 s[14:15], 0x2280000
	v_addc_co_u32_e32 v5, vcc, 0, v17, vcc
	v_lshl_add_u64 v[14:15], v[16:17], 0, s[14:15]
	v_add_co_u32_e32 v16, vcc, 0x2280000, v16
	global_load_dwordx4 v[4:7], v[4:5], off
	s_nop 0
	global_load_dwordx4 v[8:11], v[24:25], off offset:16
	v_addc_co_u32_e32 v17, vcc, 0, v17, vcc
	global_load_dwordx4 v[16:19], v[16:17], off
	s_nop 0
	global_load_dwordx4 v[20:23], v[14:15], off offset:16
	global_load_dwordx4 v[230:233], v[24:25], off offset:64
	global_load_dwordx4 v[234:237], v[24:25], off offset:80
	global_load_dwordx4 v[238:241], v[14:15], off offset:64
	global_load_dwordx4 v[242:245], v[14:15], off offset:80
	v_and_b32_e32 v29, 0xffff0000, v108
	v_lshlrev_b32_e32 v28, 16, v108
	v_and_b32_e32 v27, 0xffff0000, v112
	v_lshlrev_b32_e32 v26, 16, v112
	v_ffbl_b32_e32 v2, v13
	s_add_u32 s14, s0, s2
	v_add_u32_e32 v2, 32, v2
	s_addc_u32 s15, s1, s3
	s_add_u32 s88, s14, 0x8400000
	s_addc_u32 s89, s15, 0
	s_add_u32 s90, s14, 0x9400000
	s_addc_u32 s91, s15, 0
	s_mov_b32 s6, 0
	s_mov_b64 s[14:15], 0
	v_ffbl_b32_e32 v246, v12
	v_min_u32_e32 v52, v246, v2
	v_lshl_add_u32 v246, v52, 6, v140
	v_ashrrev_i32_e32 v247, 31, v246
	v_lshlrev_b64 v[246:247], 7, v[246:247]
	v_lshl_or_b32 v246, v138, 1, v246
	v_lshl_add_u64 v[248:249], s[88:89], 0, v[246:247]
	v_lshl_add_u64 v[246:247], s[90:91], 0, v[246:247]
	global_load_dwordx4 v[54:57], v[248:249], off
	global_load_dwordx4 v[58:61], v[246:247], off
	s_waitcnt vmcnt(6) lgkmcnt(0)
	v_pk_mul_f32 v[30:31], v[16:17], v[28:29]
	s_nop 0
	v_pk_fma_f32 v[30:31], v[4:5], v[26:27], v[30:31] neg_lo:[0,0,1] neg_hi:[0,0,1]
	v_pk_mul_f32 v[16:17], v[16:17], v[26:27]
	v_and_b32_e32 v27, 0xffff0000, v109
	v_lshlrev_b32_e32 v26, 16, v109
	v_pk_fma_f32 v[4:5], v[4:5], v[28:29], v[16:17]
	v_and_b32_e32 v17, 0xffff0000, v113
	v_lshlrev_b32_e32 v16, 16, v113
	v_pk_mul_f32 v[28:29], v[18:19], v[26:27]
	v_cvt_pk_bf16_f32 v86, v4, v5
	v_pk_fma_f32 v[28:29], v[6:7], v[16:17], v[28:29] neg_lo:[0,0,1] neg_hi:[0,0,1]
	v_pk_mul_f32 v[16:17], v[18:19], v[16:17]
	v_and_b32_e32 v19, 0xffff0000, v110
	v_lshlrev_b32_e32 v18, 16, v110
	v_pk_fma_f32 v[6:7], v[6:7], v[26:27], v[16:17]
	v_and_b32_e32 v17, 0xffff0000, v114
	v_lshlrev_b32_e32 v16, 16, v114
	v_pk_mul_f32 v[26:27], v[20:21], v[18:19]
	v_cvt_pk_bf16_f32 v87, v6, v7
	v_pk_fma_f32 v[26:27], v[8:9], v[16:17], v[26:27] neg_lo:[0,0,1] neg_hi:[0,0,1]
	v_pk_mul_f32 v[16:17], v[20:21], v[16:17]
	v_cvt_pk_bf16_f32 v84, v26, v27
	v_pk_fma_f32 v[8:9], v[8:9], v[18:19], v[16:17]
	v_and_b32_e32 v19, 0xffff0000, v111
	v_lshlrev_b32_e32 v18, 16, v111
	v_and_b32_e32 v17, 0xffff0000, v115
	v_lshlrev_b32_e32 v16, 16, v115
	v_pk_mul_f32 v[20:21], v[22:23], v[18:19]
	v_cvt_pk_bf16_f32 v88, v8, v9
	v_pk_fma_f32 v[20:21], v[10:11], v[16:17], v[20:21] neg_lo:[0,0,1] neg_hi:[0,0,1]
	v_pk_mul_f32 v[16:17], v[22:23], v[16:17]
	v_cvt_pk_bf16_f32 v85, v20, v21
	v_pk_fma_f32 v[10:11], v[10:11], v[18:19], v[16:17]
	v_cvt_pk_bf16_f32 v82, v30, v31
	v_cvt_pk_bf16_f32 v89, v10, v11
	v_and_b32_e32 v25, 0xffff0000, v104
	v_lshlrev_b32_e32 v24, 16, v104
	v_and_b32_e32 v15, 0xffff0000, v100
	v_lshlrev_b32_e32 v14, 16, v100
	v_cvt_pk_bf16_f32 v83, v28, v29
	s_waitcnt vmcnt(2) lgkmcnt(0)
	v_pk_mul_f32 v[26:27], v[238:239], v[24:25]
	s_nop 0
	v_pk_fma_f32 v[26:27], v[230:231], v[14:15], v[26:27] neg_lo:[0, 0, 1] neg_hi:[0, 0, 1]
	v_pk_mul_f32 v[14:15], v[238:239], v[14:15]
	v_and_b32_e32 v17, 0xffff0000, v105
	v_lshlrev_b32_e32 v16, 16, v105
	v_pk_fma_f32 v[8:9], v[230:231], v[24:25], v[14:15]
	v_and_b32_e32 v15, 0xffff0000, v101
	v_lshlrev_b32_e32 v14, 16, v101
	v_pk_mul_f32 v[24:25], v[240:241], v[16:17]
	v_cvt_pk_bf16_f32 v90, v26, v27
	v_pk_fma_f32 v[24:25], v[232:233], v[14:15], v[24:25] neg_lo:[0, 0, 1] neg_hi:[0, 0, 1]
	v_pk_mul_f32 v[14:15], v[240:241], v[14:15]
	v_cvt_pk_bf16_f32 v91, v24, v25
	v_pk_fma_f32 v[10:11], v[232:233], v[16:17], v[14:15]
	v_and_b32_e32 v17, 0xffff0000, v106
	v_lshlrev_b32_e32 v16, 16, v106
	v_and_b32_e32 v15, 0xffff0000, v102
	v_lshlrev_b32_e32 v14, 16, v102
	v_pk_mul_f32 v[18:19], v[242:243], v[16:17]
	v_cvt_pk_bf16_f32 v94, v8, v9
	v_pk_fma_f32 v[18:19], v[234:235], v[14:15], v[18:19] neg_lo:[0, 0, 1] neg_hi:[0, 0, 1]
	v_pk_mul_f32 v[14:15], v[242:243], v[14:15]
	v_cvt_pk_bf16_f32 v92, v18, v19
	v_pk_fma_f32 v[4:5], v[234:235], v[16:17], v[14:15]
	v_and_b32_e32 v17, 0xffff0000, v107
	v_cvt_pk_bf16_f32 v96, v4, v5
	v_lshl_add_u64 v[4:5], v[12:13], 0, -1
	v_lshlrev_b32_e32 v16, 16, v107
	v_and_b32_e32 v50, v4, v12
	v_and_b32_e32 v15, 0xffff0000, v103
	v_lshlrev_b32_e32 v14, 16, v103
	v_pk_mul_f32 v[20:21], v[244:245], v[16:17]
	v_and_b32_e32 v51, v5, v13
	v_pk_fma_f32 v[20:21], v[236:237], v[14:15], v[20:21] neg_lo:[0, 0, 1] neg_hi:[0, 0, 1]
	v_pk_mul_f32 v[14:15], v[244:245], v[14:15]
	v_pk_fma_f32 v[6:7], v[236:237], v[16:17], v[14:15]
	v_cvt_pk_bf16_f32 v97, v6, v7
	v_mov_b32_e32 v16, v3
	v_mov_b32_e32 v17, v3
	v_cvt_pk_bf16_f32 v93, v20, v21
	v_cvt_pk_bf16_f32 v95, v10, v11
	v_mov_b32_e32 v2, v3
	v_mov_b32_e32 v4, v3
	v_mov_b32_e32 v5, v3
	v_mov_b32_e32 v6, v3
	v_mov_b32_e32 v7, v3
	v_mov_b32_e32 v8, v3
	v_mov_b32_e32 v9, v3
	v_mov_b32_e32 v10, v3
	v_mov_b32_e32 v11, v3
	v_mov_b32_e32 v12, v3
	v_mov_b32_e32 v13, v3
	v_mov_b32_e32 v14, v3
	v_mov_b32_e32 v15, v3
	v_mov_b64_e32 v[32:33], v[16:17]
	v_mov_b64_e32 v[48:49], v[16:17]
	v_mov_b32_e32 v107, 0xf149f2ca
	v_mov_b32_e32 v106, 0
	v_mov_b64_e32 v[30:31], v[14:15]
	v_mov_b64_e32 v[28:29], v[12:13]
	v_mov_b64_e32 v[26:27], v[10:11]
	v_mov_b64_e32 v[24:25], v[8:9]
	v_mov_b64_e32 v[22:23], v[6:7]
	v_mov_b64_e32 v[20:21], v[4:5]
	v_mov_b64_e32 v[18:19], v[2:3]
	v_mov_b64_e32 v[46:47], v[14:15]
	v_mov_b64_e32 v[44:45], v[12:13]
	v_mov_b64_e32 v[42:43], v[10:11]
	v_mov_b64_e32 v[40:41], v[8:9]
	v_mov_b64_e32 v[38:39], v[6:7]
	v_mov_b64_e32 v[36:37], v[4:5]
	v_mov_b64_e32 v[34:35], v[2:3]
	s_waitcnt vmcnt(0)
	v_mov_b64_e32 v[98:99], v[54:55]
	v_mov_b64_e32 v[100:101], v[56:57]
	v_mov_b64_e32 v[102:103], v[58:59]
	v_mov_b64_e32 v[104:105], v[60:61]
	v_readfirstlane_b32 s98, v50
	v_readfirstlane_b32 s99, v51
	v_readfirstlane_b32 s100, v52
	s_branch .LBB0_1181
